# GEMM phase prologue: second K-tile LDS-DMA loads issued right behind the first (before the first wait/barrier) in all 9 GEMM phase prologues
# baseline (speedup 1.0000x reference)
; #define PG8_STAGE(bufoff, gbase, voff) do { _Pragma("unroll") for (int _i = 0; _i < 2; ++_i) \
;         __builtin_amdgcn_global_load_lds((const unsigned*)((const char*)(gbase) + (voff)[_i]), (LAS unsigned*)(lds + (bufoff) + ldsw + _i * 8192), 16, 0, 0); } while (0)
; #define PG8_WAIT_V(n) asm volatile("s_waitcnt vmcnt(" #n ")" ::: "memory")
; #define PG8_BAR __builtin_amdgcn_s_barrier()
; template <class GEO, class Epi>
; __device__ __forceinline__ void gemm_phase(LAS unsigned char* lds, const Gemm g, const StaticOrder& S, const Epi& E) {
;     ...
;     for (int i = 0; i < 2; ++i) { int R, C; stage_rc(tid * 16 + i * 8192, R, C); const int Rb = Epi::PERM ? ((R & ~31) + perm32(R & 31)) : R;
;         voffA[i] = (unsigned)(R * GEO::LDA + C) * 2u; voffB[i] = (unsigned)(Rb * GEO::LDB + C) * 2u; }
;     const size_t kstep = (size_t)(BK * 2);
;     constexpr size_t hstepA = (size_t)HALF * GEO::LDA * 2, hstepB = (size_t)HALF * GEO::LDB * 2;
;     const unsigned ldsw = (unsigned)wid * 1024u;
;     const int aoff = lds_byte(wr * 64 + fr, fq * 8), boff = lds_byte(wc * 32 + fr, fq * 8);
;     ...
;     PG8_STAGE(PG8_SB(0, 0), cB, voffB); PG8_STAGE(PG8_SB(0, 1), cB + hstepB, voffB); PG8_STAGE(PG8_SA(0, 0), cA, voffA); PG8_STAGE(PG8_SA(0, 1), cA + hstepA, voffA);
;     if (wr == 1) PG8_BAR;
;     PG8_WAIT_V(2); PG8_BAR;
;     PG8_STAGE(PG8_SB(1, 0), cB + kstep, voffB); PG8_STAGE(PG8_SA(1, 0), cA + kstep, voffA); PG8_STAGE(PG8_SB(1, 1), cB + hstepB + kstep, voffB);
;     PG8_WAIT_V(6); PG8_BAR;
.LBB0_159:
	s_mov_b64 s[42:43], 0x80
	s_and_b32 s20, s7, 3
	s_add_i32 m0, s19, 0x18000
	v_lshl_add_u64 v[6:7], v[6:7], 0, s[42:43]
	s_lshl_b32 s21, s13, 13
	s_lshl_b32 s22, s20, 5
	s_lshl_b32 s34, s20, 12
	global_load_lds_dwordx4 v[6:7], off
	v_lshl_add_u64 v[4:5], v[4:5], 0, s[42:43]
	s_add_i32 m0, s19, 0x1a000
	s_add_i32 s85, s19, 0x8000
	s_add_i32 s86, s19, 0xa000
	global_load_lds_dwordx4 v[4:5], off
	v_lshl_add_u64 v[0:1], v[0:1], 0, s[42:43]
	s_mov_b32 m0, s85
	s_add_u32 s4, s88, 0x40080
	global_load_lds_dwordx4 v[0:1], off
	v_lshl_add_u64 v[0:1], v[2:3], 0, s[42:43]
	s_mov_b32 m0, s86
	s_addc_u32 s5, s89, 0
	global_load_lds_dwordx4 v[0:1], off
	s_add_i32 m0, s19, 0x1c000
	v_lshl_add_u64 v[0:1], s[4:5], 0, v[140:141]
	global_load_lds_dwordx4 v[0:1], off
	v_lshl_add_u64 v[0:1], s[4:5], 0, v[144:145]
	s_add_i32 m0, s19, 0x1e000
	v_bfe_u32 v17, v8, 4, 2
	global_load_lds_dwordx4 v[0:1], off
	s_waitcnt vmcnt(8)
	s_barrier
	v_and_b32_e32 v15, 15, v8
	v_lshlrev_b32_e32 v18, 4, v17
	v_lshlrev_b32_e32 v0, 2, v8
	v_lshl_or_b32 v18, v15, 6, v18
	v_and_b32_e32 v0, 32, v0
	v_bitop3_b32 v2, v18, s21, v0 bitop3:0xde
	v_bitop3_b32 v163, v18, s34, v0 bitop3:0xde
	v_lshlrev_b32_e32 v0, 5, v17
	v_mov_b32_e32 v1, v141
	v_lshl_add_u64 v[146:147], s[60:61], 0, v[0:1]
	v_lshlrev_b32_e32 v0, 14, v9
	v_and_b32_e32 v0, 0xffff8000, v0
	s_cmpk_lt_u32 s6, 0x100
	v_lshl_add_u32 v0, v10, 11, v0
	v_and_b32_e32 v1, 1, v9
	s_cselect_b64 s[44:45], -1, 0
	s_add_i32 s6, 0, 0x20000
	s_lshl_b32 s21, s20, 2
	s_and_b32 s7, s7, 2
	v_lshl_or_b32 v0, v1, 6, v0
	v_lshl_or_b32 v162, s13, 6, v15
	s_add_i32 s21, s6, s21
	s_lshl_b32 s13, s13, 11
	s_lshl_b32 s7, s7, 2
	v_lshl_add_u32 v148, v11, 1, v0
	v_lshlrev_b32_e32 v0, 14, v12
	s_add_i32 s21, s21, s13
	s_and_b32 s13, s22, 32
	s_add_i32 s6, s6, s7
	v_and_b32_e32 v0, 0xffff8000, v0
	s_waitcnt vmcnt(6)
	v_or_b32_e32 v164, 16, v162
	v_or_b32_e32 v165, 32, v162
	v_or_b32_e32 v166, 48, v162
	v_add_u32_e32 v167, 0x80, v162
	v_add_u32_e32 v168, 0x90, v162
	v_add_u32_e32 v169, 0xa0, v162
	v_add_u32_e32 v170, 0xb0, v162
	s_cmp_eq_u32 s20, 0
	v_lshl_add_u32 v0, v13, 11, v0
	v_and_b32_e32 v1, 1, v12
	v_lshlrev_b32_e32 v16, 3, v17
	v_lshlrev_b32_e32 v3, 5, v15
	v_lshlrev_b32_e32 v4, 5, v162
	v_lshlrev_b32_e32 v5, 5, v164
	v_lshlrev_b32_e32 v6, 5, v165
	v_lshlrev_b32_e32 v7, 5, v166
	v_lshlrev_b32_e32 v8, 5, v167
	v_lshlrev_b32_e32 v15, 5, v168
	v_lshlrev_b32_e32 v18, 5, v169
	v_lshlrev_b32_e32 v19, 5, v170
	s_cselect_b64 s[46:47], -1, 0
	v_lshl_or_b32 v0, v1, 6, v0
	s_add_i32 s87, 0, 0x10000
	s_add_i32 s90, 0, 0x14000
	v_cmp_eq_u32_e64 s[4:5], 0, v17
	v_or_b32_e32 v171, s22, v16
	v_mov_b32_e32 v149, v141
	v_lshl_add_u32 v150, v14, 1, v0
	v_mov_b32_e32 v151, v141
	v_mov_b64_e32 v[152:153], 0x680
	v_mov_b64_e32 v[154:155], 0x67f
	v_add_u32_e32 v172, s87, v163
	v_add_u32_e32 v173, s90, v163
	v_add_u32_e32 v174, 0, v2
	s_movk_i32 s91, 0x1a00
	s_lshl_b32 s94, s13, 2
	v_lshlrev_b32_e32 v175, 2, v16
	v_add_u32_e32 v176, s6, v4
	s_mov_b32 s48, 0x3c800000
	s_mov_b32 s95, 0x800000
	v_add_u32_e32 v177, s6, v5
	v_add_u32_e32 v178, s6, v6
	v_add_u32_e32 v179, s6, v7
	v_add_u32_e32 v180, s6, v8
	v_add_u32_e32 v181, s6, v15
	v_add_u32_e32 v182, s6, v18
	v_add_u32_e32 v183, s6, v19
	v_add_u32_e32 v184, s21, v3
	v_mov_b32_e32 v185, 0x3e38aa3b
	s_mov_b32 s81, 0
	s_barrier
	s_branch .LBB0_162

; #define PG8_STAGE(bufoff, gbase, voff) do { _Pragma("unroll") for (int _i = 0; _i < 2; ++_i) \
;         __builtin_amdgcn_global_load_lds((const unsigned*)((const char*)(gbase) + (voff)[_i]), (LAS unsigned*)(lds + (bufoff) + ldsw + _i * 8192), 16, 0, 0); } while (0)
; #define PG8_WAIT_V(n) asm volatile("s_waitcnt vmcnt(" #n ")" ::: "memory")
; #define PG8_BAR __builtin_amdgcn_s_barrier()
; template <class GEO, class Epi>
; __device__ __forceinline__ void gemm_phase(LAS unsigned char* lds, const Gemm g, const StaticOrder& S, const Epi& E) {
;     ...
;     for (int i = 0; i < 2; ++i) { int R, C; stage_rc(tid * 16 + i * 8192, R, C); const int Rb = Epi::PERM ? ((R & ~31) + perm32(R & 31)) : R;
;         voffA[i] = (unsigned)(R * GEO::LDA + C) * 2u; voffB[i] = (unsigned)(Rb * GEO::LDB + C) * 2u; }
;     const size_t kstep = (size_t)(BK * 2);
;     constexpr size_t hstepA = (size_t)HALF * GEO::LDA * 2, hstepB = (size_t)HALF * GEO::LDB * 2;
;     const unsigned ldsw = (unsigned)wid * 1024u;
;     const int aoff = lds_byte(wr * 64 + fr, fq * 8), boff = lds_byte(wc * 32 + fr, fq * 8);
;     ...
;     PG8_STAGE(PG8_SB(0, 0), cB, voffB); PG8_STAGE(PG8_SB(0, 1), cB + hstepB, voffB); PG8_STAGE(PG8_SA(0, 0), cA, voffA); PG8_STAGE(PG8_SA(0, 1), cA + hstepA, voffA);
;     if (wr == 1) PG8_BAR;
;     PG8_WAIT_V(2); PG8_BAR;
;     PG8_STAGE(PG8_SB(1, 0), cB + kstep, voffB); PG8_STAGE(PG8_SA(1, 0), cA + kstep, voffA); PG8_STAGE(PG8_SB(1, 1), cB + hstepB + kstep, voffB);
;     PG8_WAIT_V(6); PG8_BAR;
.LBB0_222:
	s_mov_b64 s[22:23], 0x80
	s_and_b32 s6, s4, 3
	s_add_i32 m0, s79, 0x18000
	v_lshl_add_u64 v[6:7], v[6:7], 0, s[22:23]
	s_lshl_b32 s9, s8, 13
	s_lshl_b32 s42, s6, 5
	s_lshl_b32 s13, s6, 12
	global_load_lds_dwordx4 v[6:7], off
	v_lshl_add_u64 v[4:5], v[4:5], 0, s[22:23]
	s_add_i32 m0, s79, 0x1a000
	s_add_i32 s86, s79, 0x8000
	s_add_i32 s87, s79, 0xa000
	global_load_lds_dwordx4 v[4:5], off
	v_lshl_add_u64 v[0:1], v[0:1], 0, s[22:23]
	s_mov_b32 m0, s86
	s_add_u32 s4, s88, 0x40080
	global_load_lds_dwordx4 v[0:1], off
	v_lshl_add_u64 v[0:1], v[2:3], 0, s[22:23]
	s_mov_b32 m0, s87
	s_addc_u32 s5, s89, 0
	global_load_lds_dwordx4 v[0:1], off
	s_add_i32 m0, s79, 0x1c000
	v_lshl_add_u64 v[0:1], s[4:5], 0, v[140:141]
	global_load_lds_dwordx4 v[0:1], off
	v_lshl_add_u64 v[0:1], s[4:5], 0, v[144:145]
	s_add_i32 m0, s79, 0x1e000
	v_bfe_u32 v2, v8, 4, 2
	global_load_lds_dwordx4 v[0:1], off
	s_waitcnt vmcnt(8)
	s_barrier
	v_and_b32_e32 v1, 15, v8
	v_lshlrev_b32_e32 v3, 4, v2
	v_lshl_or_b32 v160, s8, 6, v1
	v_lshl_or_b32 v3, v1, 6, v3
	v_lshlrev_b32_e32 v4, 2, v8
	v_lshlrev_b32_e32 v162, 4, v1
	v_lshlrev_b32_e32 v1, 14, v9
	v_and_b32_e32 v4, 32, v4
	v_and_b32_e32 v1, 0xffff8000, v1
	v_bitop3_b32 v5, v3, s9, v4 bitop3:0xde
	v_bitop3_b32 v161, v3, s13, v4 bitop3:0xde
	v_lshl_add_u32 v1, v10, 11, v1
	v_and_b32_e32 v3, 1, v9
	v_lshl_or_b32 v1, v3, 6, v1
	s_cmpk_lt_u32 s12, 0x100
	v_lshl_add_u32 v150, v11, 1, v1
	v_lshlrev_b32_e32 v1, 14, v12
	v_lshlrev_b32_e32 v0, 3, v2
	s_cselect_b64 s[36:37], -1, 0
	s_lshl_b32 s8, s8, 10
	v_and_b32_e32 v1, 0xffff8000, v1
	s_waitcnt vmcnt(6)
	v_cmp_eq_u32_e64 s[4:5], 0, v2
	s_add_i32 s20, s8, 0
	v_or_b32_e32 v2, s42, v0
	v_lshl_add_u32 v1, v13, 11, v1
	v_and_b32_e32 v3, 1, v12
	s_lshl_b32 s6, s6, 2
	s_add_i32 s90, s20, 0x20000
	v_lshlrev_b32_e32 v146, 2, v2
	v_lshl_or_b32 v1, v3, 6, v1
	s_add_i32 s54, 0, 0x10000
	s_add_i32 s34, 0, 0x14000
	s_add_i32 s91, s90, s6
	s_add_i32 s94, s20, 0x20100
	s_add_i32 s95, s20, 0x20200
	s_add_i32 s12, s20, 0x20300
	s_add_i32 s13, s20, 0x20800
	s_add_i32 s38, s20, 0x20900
	s_add_i32 s39, s20, 0x20a00
	s_add_i32 s20, s20, 0x20b00
	s_ashr_i32 s21, s41, 31
	v_lshl_add_u64 v[148:149], s[64:65], 0, v[146:147]
	v_mov_b32_e32 v151, v147
	v_lshl_add_u32 v152, v14, 1, v1
	v_mov_b32_e32 v153, v147
	v_add_u32_e32 v163, s54, v161
	v_add_u32_e32 v164, s34, v161
	v_add_u32_e32 v165, 0, v5
	v_lshlrev_b32_e32 v146, 1, v2
	s_mov_b32 s40, 0x3b800000
	s_mov_b32 s35, 0x800000
	s_lshl_b32 s42, s42, 1
	v_lshlrev_b32_e32 v154, 1, v0
	s_mov_b32 s82, 0
	s_barrier
	s_branch .LBB0_225

; #define PG8_STAGE(bufoff, gbase, voff) do { _Pragma("unroll") for (int _i = 0; _i < 2; ++_i) \
;         __builtin_amdgcn_global_load_lds((const unsigned*)((const char*)(gbase) + (voff)[_i]), (LAS unsigned*)(lds + (bufoff) + ldsw + _i * 8192), 16, 0, 0); } while (0)
; #define PG8_WAIT_V(n) asm volatile("s_waitcnt vmcnt(" #n ")" ::: "memory")
; #define PG8_BAR __builtin_amdgcn_s_barrier()
; template <class GEO, class Epi>
; __device__ __forceinline__ void gemm_phase(LAS unsigned char* lds, const Gemm g, const StaticOrder& S, const Epi& E) {
;     ...
;     PG8_STAGE(PG8_SB(0, 0), cB, voffB); PG8_STAGE(PG8_SB(0, 1), cB + hstepB, voffB); PG8_STAGE(PG8_SA(0, 0), cA, voffA); PG8_STAGE(PG8_SA(0, 1), cA + hstepA, voffA);
;     if (wr == 1) PG8_BAR;
;     PG8_WAIT_V(2); PG8_BAR;
;     PG8_STAGE(PG8_SB(1, 0), cB + kstep, voffB); PG8_STAGE(PG8_SA(1, 0), cA + kstep, voffA); PG8_STAGE(PG8_SB(1, 1), cB + hstepB + kstep, voffB);
;     PG8_WAIT_V(6); PG8_BAR;
.LBB0_415:
	v_lshrrev_b32_e32 v10, 1, v8
	v_and_b32_e32 v10, 24, v10
	v_and_b32_e32 v9, 15, v8
	v_lshlrev_b32_e32 v11, 1, v10
	v_lshlrev_b32_e32 v8, 2, v8
	v_lshl_or_b32 v136, s8, 6, v9
	v_lshl_or_b32 v9, v9, 6, v11
	s_lshl_b32 s8, s8, 13
	v_and_b32_e32 v8, 32, v8
	v_bitop3_b32 v11, v9, s8, v8 bitop3:0xde
	s_lshl_b32 s8, s9, 5
	s_mov_b64 s[22:23], 0x80
	s_and_b32 s34, s8, 0x60
	s_add_i32 m0, s5, 0x18000
	v_lshl_add_u64 v[6:7], v[6:7], 0, s[22:23]
	s_lshl_b32 s8, s34, 7
	global_load_lds_dwordx4 v[6:7], off
	v_lshl_add_u64 v[4:5], v[4:5], 0, s[22:23]
	s_add_i32 m0, s5, 0x1a000
	s_add_i32 s18, s5, 0x8000
	s_add_i32 s19, s5, 0xa000
	v_bitop3_b32 v137, v9, s8, v8 bitop3:0xde
	global_load_lds_dwordx4 v[4:5], off
	v_lshl_add_u64 v[0:1], v[0:1], 0, s[22:23]
	s_mov_b32 m0, s18
	s_add_u32 s8, s40, 0x40080
	global_load_lds_dwordx4 v[0:1], off
	v_lshl_add_u64 v[0:1], v[2:3], 0, s[22:23]
	s_mov_b32 m0, s19
	s_addc_u32 s9, s41, 0
	global_load_lds_dwordx4 v[0:1], off
	s_add_i32 m0, s5, 0x1c000
	v_lshl_add_u64 v[0:1], s[8:9], 0, v[130:131]
	global_load_lds_dwordx4 v[0:1], off
	v_lshl_add_u64 v[0:1], s[8:9], 0, v[134:135]
	s_add_i32 m0, s5, 0x1e000
	s_cmpk_lt_u32 s30, 0x100
	global_load_lds_dwordx4 v[0:1], off
	s_waitcnt vmcnt(8)
	s_barrier
	s_waitcnt vmcnt(6)
	s_cselect_b64 s[30:31], -1, 0
	v_or_b32_e32 v138, s34, v10
	s_add_i32 s34, 0, 0x10000
	s_add_i32 s35, 0, 0x14000
	v_add_u32_e32 v139, s34, v137
	v_add_u32_e32 v140, s35, v137
	v_add_u32_e32 v141, 0, v11
	s_barrier
	s_branch .LBB0_418

; #define PG8_STAGE(bufoff, gbase, voff) do { _Pragma("unroll") for (int _i = 0; _i < 2; ++_i) \
;         __builtin_amdgcn_global_load_lds((const unsigned*)((const char*)(gbase) + (voff)[_i]), (LAS unsigned*)(lds + (bufoff) + ldsw + _i * 8192), 16, 0, 0); } while (0)
; #define PG8_WAIT_V(n) asm volatile("s_waitcnt vmcnt(" #n ")" ::: "memory")
; #define PG8_BAR __builtin_amdgcn_s_barrier()
; template <class GEO, class Epi>
; __device__ __forceinline__ void gemm_phase(LAS unsigned char* lds, const Gemm g, const StaticOrder& S, const Epi& E) {
;     ...
;     for (int i = 0; i < 2; ++i) { int R, C; stage_rc(tid * 16 + i * 8192, R, C); const int Rb = Epi::PERM ? ((R & ~31) + perm32(R & 31)) : R;
;         voffA[i] = (unsigned)(R * GEO::LDA + C) * 2u; voffB[i] = (unsigned)(Rb * GEO::LDB + C) * 2u; }
;     const size_t kstep = (size_t)(BK * 2);
;     constexpr size_t hstepA = (size_t)HALF * GEO::LDA * 2, hstepB = (size_t)HALF * GEO::LDB * 2;
;     const unsigned ldsw = (unsigned)wid * 1024u;
;     const int aoff = lds_byte(wr * 64 + fr, fq * 8), boff = lds_byte(wc * 32 + fr, fq * 8);
;     ...
;     PG8_STAGE(PG8_SB(0, 0), cB, voffB); PG8_STAGE(PG8_SB(0, 1), cB + hstepB, voffB); PG8_STAGE(PG8_SA(0, 0), cA, voffA); PG8_STAGE(PG8_SA(0, 1), cA + hstepA, voffA);
;     if (wr == 1) PG8_BAR;
;     PG8_WAIT_V(2); PG8_BAR;
;     PG8_STAGE(PG8_SB(1, 0), cB + kstep, voffB); PG8_STAGE(PG8_SA(1, 0), cA + kstep, voffA); PG8_STAGE(PG8_SB(1, 1), cB + hstepB + kstep, voffB);
;     PG8_WAIT_V(6); PG8_BAR;
.LBB0_681:
	v_bfe_u32 v17, v11, 4, 2
	v_lshrrev_b32_e32 v15, 4, v11
	v_and_b32_e32 v16, 15, v11
	v_lshlrev_b32_e32 v19, 4, v17
	v_lshlrev_b32_e32 v11, 2, v11
	s_and_b32 s9, s19, 3
	v_lshl_or_b32 v19, v16, 6, v19
	s_lshl_b32 s7, s8, 13
	v_and_b32_e32 v11, 32, v11
	s_mov_b64 s[30:31], 0x80
	v_bitop3_b32 v20, v19, s7, v11 bitop3:0xde
	s_lshl_b32 s7, s9, 12
	s_add_i32 m0, s1, 0x18000
	v_lshl_add_u64 v[6:7], v[6:7], 0, s[30:31]
	v_bitop3_b32 v149, v19, s7, v11 bitop3:0xde
	global_load_lds_dwordx4 v[6:7], off
	v_lshl_add_u64 v[4:5], v[4:5], 0, s[30:31]
	s_add_i32 m0, s1, 0x1a000
	s_add_i32 s7, s1, 0x8000
	s_add_i32 s12, s1, 0xa000
	global_load_lds_dwordx4 v[4:5], off
	v_lshl_add_u64 v[0:1], v[0:1], 0, s[30:31]
	s_mov_b32 m0, s7
	s_add_u32 s34, s56, 0x40080
	global_load_lds_dwordx4 v[0:1], off
	v_lshl_add_u64 v[0:1], v[2:3], 0, s[30:31]
	s_mov_b32 m0, s12
	s_addc_u32 s35, s57, 0
	global_load_lds_dwordx4 v[0:1], off
	s_add_i32 m0, s1, 0x1c000
	v_lshl_add_u64 v[0:1], s[34:35], 0, v[130:131]
	global_load_lds_dwordx4 v[0:1], off
	v_lshl_add_u64 v[0:1], s[34:35], 0, v[134:135]
	s_add_i32 m0, s1, 0x1e000
	s_cmpk_lt_u32 s13, 0x100
	global_load_lds_dwordx4 v[0:1], off
	s_waitcnt vmcnt(8)
	s_barrier
	v_bitop3_b32 v0, s19, v15, 3 bitop3:0xa8
	v_cmp_eq_u32_e64 s[42:43], 0, v0
	v_lshlrev_b32_e32 v0, 14, v8
	v_and_b32_e32 v0, 0xffff8000, v0
	v_lshl_add_u32 v0, v9, 11, v0
	v_and_b32_e32 v1, 1, v8
	v_lshl_or_b32 v0, v1, 6, v0
	v_lshl_add_u32 v136, v10, 1, v0
	v_lshlrev_b32_e32 v0, 14, v12
	v_lshl_or_b32 v148, s8, 6, v16
	s_cselect_b64 s[34:35], -1, 0
	s_lshl_b32 s8, s8, 10
	v_and_b32_e32 v0, 0xffff8000, v0
	v_lshlrev_b32_e32 v18, 3, v17
	s_waitcnt vmcnt(6)
	s_add_i32 s62, s8, 0
	v_lshl_add_u32 v0, v13, 11, v0
	v_and_b32_e32 v1, 1, v12
	v_lshl_or_b32 v150, s9, 5, v18
	s_lshl_b32 s9, s9, 2
	s_add_i32 s13, s62, 0x20000
	v_lshl_or_b32 v0, v1, 6, v0
	s_add_i32 s63, 0, 0x10000
	s_add_i32 s64, 0, 0x14000
	v_cmp_eq_u32_e64 s[40:41], 0, v17
	s_add_i32 s18, s13, s9
	v_lshlrev_b32_e32 v151, 4, v16
	s_add_i32 s19, s62, 0x20b00
	s_add_i32 s33, s62, 0x20a00
	s_add_i32 s36, s62, 0x20900
	s_add_i32 s37, s62, 0x20800
	s_add_i32 s60, s62, 0x20300
	s_add_i32 s61, s62, 0x20200
	s_add_i32 s62, s62, 0x20100
	v_mov_b32_e32 v137, v131
	v_lshl_add_u32 v138, v14, 1, v0
	v_mov_b32_e32 v139, v131
	v_mov_b64_e32 v[140:141], 0x200
	v_mov_b64_e32 v[142:143], 0x1ff
	v_add_u32_e32 v152, s63, v149
	v_add_u32_e32 v153, s64, v149
	v_add_u32_e32 v154, 0, v20
	s_mov_b32 s65, 0
	s_barrier
	s_branch .LBB0_684

; #define PG8_STAGE(bufoff, gbase, voff) do { _Pragma("unroll") for (int _i = 0; _i < 2; ++_i) \
;         __builtin_amdgcn_global_load_lds((const unsigned*)((const char*)(gbase) + (voff)[_i]), (LAS unsigned*)(lds + (bufoff) + ldsw + _i * 8192), 16, 0, 0); } while (0)
; #define PG8_WAIT_V(n) asm volatile("s_waitcnt vmcnt(" #n ")" ::: "memory")
; #define PG8_BAR __builtin_amdgcn_s_barrier()
; template <class GEO, class Epi>
; __device__ __forceinline__ void gemm_phase(LAS unsigned char* lds, const Gemm g, const StaticOrder& S, const Epi& E) {
;     ...
;     for (int i = 0; i < 2; ++i) { int R, C; stage_rc(tid * 16 + i * 8192, R, C); const int Rb = Epi::PERM ? ((R & ~31) + perm32(R & 31)) : R;
;         voffA[i] = (unsigned)(R * GEO::LDA + C) * 2u; voffB[i] = (unsigned)(Rb * GEO::LDB + C) * 2u; }
;     const size_t kstep = (size_t)(BK * 2);
;     constexpr size_t hstepA = (size_t)HALF * GEO::LDA * 2, hstepB = (size_t)HALF * GEO::LDB * 2;
;     const unsigned ldsw = (unsigned)wid * 1024u;
;     const int aoff = lds_byte(wr * 64 + fr, fq * 8), boff = lds_byte(wc * 32 + fr, fq * 8);
;     ...
;     PG8_STAGE(PG8_SB(0, 0), cB, voffB); PG8_STAGE(PG8_SB(0, 1), cB + hstepB, voffB); PG8_STAGE(PG8_SA(0, 0), cA, voffA); PG8_STAGE(PG8_SA(0, 1), cA + hstepA, voffA);
;     if (wr == 1) PG8_BAR;
;     PG8_WAIT_V(2); PG8_BAR;
;     PG8_STAGE(PG8_SB(1, 0), cB + kstep, voffB); PG8_STAGE(PG8_SA(1, 0), cA + kstep, voffA); PG8_STAGE(PG8_SB(1, 1), cB + hstepB + kstep, voffB);
;     PG8_WAIT_V(6); PG8_BAR;
.LBB0_769:
	v_bfe_u32 v16, v14, 4, 2
	s_cmp_lg_u64 s[76:77], 0
	v_and_b32_e32 v15, 15, v14
	v_lshlrev_b32_e32 v18, 4, v16
	v_lshlrev_b32_e32 v14, 2, v14
	s_cselect_b64 s[22:23], -1, 0
	s_and_b32 s9, s7, 3
	v_lshl_or_b32 v18, v15, 6, v18
	s_lshl_b32 s7, s8, 13
	v_and_b32_e32 v14, 32, v14
	s_mov_b64 s[28:29], 0x80
	v_bitop3_b32 v19, v18, s7, v14 bitop3:0xde
	s_lshl_b32 s7, s9, 12
	s_add_i32 m0, s1, 0x18000
	v_lshl_add_u64 v[6:7], v[6:7], 0, s[28:29]
	v_bitop3_b32 v175, v18, s7, v14 bitop3:0xde
	global_load_lds_dwordx4 v[6:7], off
	v_lshl_add_u64 v[4:5], v[4:5], 0, s[28:29]
	s_add_i32 m0, s1, 0x1a000
	s_add_i32 s7, s1, 0x8000
	s_add_i32 s12, s1, 0xa000
	global_load_lds_dwordx4 v[4:5], off
	v_lshl_add_u64 v[0:1], v[0:1], 0, s[28:29]
	s_mov_b32 m0, s7
	s_add_u32 s18, s54, 0x40080
	global_load_lds_dwordx4 v[0:1], off
	v_lshl_add_u64 v[0:1], v[2:3], 0, s[28:29]
	s_mov_b32 m0, s12
	s_addc_u32 s19, s55, 0
	global_load_lds_dwordx4 v[0:1], off
	s_add_i32 m0, s1, 0x1c000
	v_lshl_add_u64 v[0:1], s[18:19], 0, v[130:131]
	global_load_lds_dwordx4 v[0:1], off
	v_lshl_add_u64 v[0:1], s[18:19], 0, v[134:135]
	s_add_i32 m0, s1, 0x1e000
	v_and_b32_e32 v2, 1, v8
	global_load_lds_dwordx4 v[0:1], off
	s_waitcnt vmcnt(8)
	s_barrier
	v_lshlrev_b32_e32 v1, 14, v8
	v_and_b32_e32 v1, 0xffff8000, v1
	v_lshl_add_u32 v1, v9, 11, v1
	v_lshl_or_b32 v1, v2, 6, v1
	s_cmpk_lt_u32 s13, 0x100
	v_lshl_add_u32 v140, v10, 1, v1
	v_lshlrev_b32_e32 v1, 14, v11
	v_lshl_or_b32 v173, s8, 6, v15
	v_lshlrev_b32_e32 v17, 3, v16
	s_cselect_b64 s[30:31], -1, 0
	s_lshl_b32 s8, s8, 10
	v_readlane_b32 s80, v254, 0
	v_and_b32_e32 v1, 0xffff8000, v1
	s_waitcnt vmcnt(6)
	s_add_i32 s59, s8, 0
	v_lshl_or_b32 v0, s9, 5, v17
	v_readlane_b32 s92, v254, 12
	v_readlane_b32 s93, v254, 13
	v_lshl_add_u32 v1, v12, 11, v1
	v_and_b32_e32 v2, 1, v11
	s_lshl_b32 s16, s9, 2
	s_add_i32 s13, s59, 0x20000
	v_lshlrev_b32_e32 v136, 2, v0
	v_readlane_b32 s81, v254, 1
	v_readlane_b32 s94, v254, 14
	v_readlane_b32 s95, v254, 15
	v_lshl_or_b32 v1, v2, 6, v1
	s_add_i32 s60, 0, 0x10000
	s_add_i32 s61, 0, 0x14000
	v_readlane_b32 s70, v253, 46
	v_readlane_b32 s92, v253, 2
	v_cmp_eq_u32_e64 s[40:41], 0, v16
	s_add_i32 s18, s13, s16
	v_lshlrev_b32_e32 v177, 4, v15
	s_add_i32 s19, s59, 0x20100
	s_add_i32 s33, s59, 0x20200
	s_add_i32 s35, s59, 0x20300
	s_add_i32 s36, s59, 0x20800
	s_add_i32 s37, s59, 0x20900
	s_add_i32 s58, s59, 0x20a00
	s_add_i32 s59, s59, 0x20b00
	v_lshl_add_u64 v[138:139], s[94:95], 0, v[136:137]
	v_mov_b32_e32 v141, v137
	v_lshl_add_u32 v142, v13, 1, v1
	v_mov_b32_e32 v143, v137
	v_mov_b64_e32 v[144:145], 0x200
	v_mov_b64_e32 v[146:147], 0x1ff
	v_add_u32_e32 v179, s60, v175
	v_add_u32_e32 v181, s61, v175
	v_add_u32_e32 v183, 0, v19
	v_mov_b32_e32 v185, 0x358637bd
	s_mov_b32 s62, 0x800000
	v_lshlrev_b32_e32 v136, 1, v0
	s_mov_b32 s34, 0x3b800000
	s_mov_b32 s63, 0
	v_readlane_b32 s71, v253, 47
	v_readlane_b32 s93, v253, 3
	s_mov_b64 s[80:81], s[38:39]
	s_barrier
	v_readlane_b32 s82, v254, 2
	v_readlane_b32 s83, v254, 3
	v_readlane_b32 s84, v254, 4
	v_readlane_b32 s85, v254, 5
	v_readlane_b32 s86, v254, 6
	v_readlane_b32 s87, v254, 7
	v_readlane_b32 s88, v254, 8
	v_readlane_b32 s89, v254, 9
	v_readlane_b32 s90, v254, 10
	v_readlane_b32 s91, v254, 11
	s_branch .LBB0_772

; #define PG8_STAGE(bufoff, gbase, voff) do { _Pragma("unroll") for (int _i = 0; _i < 2; ++_i) \
;         __builtin_amdgcn_global_load_lds((const unsigned*)((const char*)(gbase) + (voff)[_i]), (LAS unsigned*)(lds + (bufoff) + ldsw + _i * 8192), 16, 0, 0); } while (0)
; #define PG8_WAIT_V(n) asm volatile("s_waitcnt vmcnt(" #n ")" ::: "memory")
; #define PG8_BAR __builtin_amdgcn_s_barrier()
; template <class GEO, class Epi>
; __device__ __forceinline__ void gemm_phase(LAS unsigned char* lds, const Gemm g, const StaticOrder& S, const Epi& E) {
;     ...
;     for (int i = 0; i < 2; ++i) { int R, C; stage_rc(tid * 16 + i * 8192, R, C); const int Rb = Epi::PERM ? ((R & ~31) + perm32(R & 31)) : R;
;         voffA[i] = (unsigned)(R * GEO::LDA + C) * 2u; voffB[i] = (unsigned)(Rb * GEO::LDB + C) * 2u; }
;     const size_t kstep = (size_t)(BK * 2);
;     constexpr size_t hstepA = (size_t)HALF * GEO::LDA * 2, hstepB = (size_t)HALF * GEO::LDB * 2;
;     const unsigned ldsw = (unsigned)wid * 1024u;
;     const int aoff = lds_byte(wr * 64 + fr, fq * 8), boff = lds_byte(wc * 32 + fr, fq * 8);
;     ...
;     PG8_STAGE(PG8_SB(0, 0), cB, voffB); PG8_STAGE(PG8_SB(0, 1), cB + hstepB, voffB); PG8_STAGE(PG8_SA(0, 0), cA, voffA); PG8_STAGE(PG8_SA(0, 1), cA + hstepA, voffA);
;     if (wr == 1) PG8_BAR;
;     PG8_WAIT_V(2); PG8_BAR;
;     PG8_STAGE(PG8_SB(1, 0), cB + kstep, voffB); PG8_STAGE(PG8_SA(1, 0), cA + kstep, voffA); PG8_STAGE(PG8_SB(1, 1), cB + hstepB + kstep, voffB);
;     PG8_WAIT_V(6); PG8_BAR;
.LBB0_872:
	v_bfe_u32 v10, v8, 4, 2
	v_and_b32_e32 v9, 15, v8
	v_lshlrev_b32_e32 v12, 4, v10
	v_lshlrev_b32_e32 v8, 2, v8
	s_and_b32 s9, s7, 3
	v_lshl_or_b32 v12, v9, 6, v12
	s_lshl_b32 s7, s8, 13
	v_and_b32_e32 v8, 32, v8
	s_mov_b64 s[28:29], 0x80
	v_bitop3_b32 v13, v12, s7, v8 bitop3:0xde
	s_lshl_b32 s7, s9, 12
	s_add_i32 m0, s22, 0x18000
	v_lshl_add_u64 v[4:5], v[4:5], 0, s[28:29]
	v_bitop3_b32 v175, v12, s7, v8 bitop3:0xde
	global_load_lds_dwordx4 v[4:5], off
	v_lshl_add_u64 v[2:3], v[2:3], 0, s[28:29]
	s_add_i32 m0, s22, 0x1a000
	s_add_i32 s7, s22, 0x8000
	s_add_i32 s12, s22, 0xa000
	global_load_lds_dwordx4 v[2:3], off
	v_lshl_add_u64 v[0:1], v[0:1], 0, s[28:29]
	s_mov_b32 m0, s7
	s_add_u32 s18, s52, 0x40080
	global_load_lds_dwordx4 v[0:1], off
	v_lshl_add_u64 v[0:1], v[6:7], 0, s[28:29]
	s_mov_b32 m0, s12
	s_addc_u32 s19, s53, 0
	global_load_lds_dwordx4 v[0:1], off
	s_add_i32 m0, s22, 0x1c000
	v_lshl_add_u64 v[0:1], s[18:19], 0, v[150:151]
	global_load_lds_dwordx4 v[0:1], off
	v_lshl_add_u64 v[0:1], s[18:19], 0, v[154:155]
	s_add_i32 m0, s22, 0x1e000
	s_cmpk_lt_u32 s13, 0x100
	global_load_lds_dwordx4 v[0:1], off
	s_waitcnt vmcnt(8)
	s_barrier
	v_lshl_or_b32 v174, s8, 6, v9
	s_cselect_b64 s[30:31], -1, 0
	s_lshl_b32 s8, s8, 10
	v_lshlrev_b32_e32 v11, 3, v10
	s_waitcnt vmcnt(6)
	s_add_i32 s84, s8, 0
	s_lshl_b32 s20, s9, 2
	s_add_i32 s13, s84, 0x20000
	s_add_i32 s19, s84, 0x21000
	v_lshl_or_b32 v0, s9, 5, v11
	s_add_i32 s85, 0, 0x10000
	s_add_i32 s86, 0, 0x14000
	v_cmp_eq_u32_e64 s[40:41], 0, v10
	s_add_i32 s18, s13, s20
	v_lshlrev_b32_e32 v176, 4, v9
	s_add_i32 s33, s19, s20
	s_add_i32 s35, s84, 0x20100
	s_add_i32 s36, s84, 0x20200
	s_add_i32 s37, s84, 0x20300
	s_add_i32 s70, s84, 0x20800
	s_add_i32 s71, s84, 0x20900
	s_add_i32 s72, s84, 0x20a00
	s_add_i32 s73, s84, 0x20b00
	s_add_i32 s78, s84, 0x21100
	s_add_i32 s79, s84, 0x21200
	s_add_i32 s80, s84, 0x21300
	s_add_i32 s81, s84, 0x21800
	s_add_i32 s82, s84, 0x21900
	s_add_i32 s83, s84, 0x21a00
	s_add_i32 s84, s84, 0x21b00
	v_mov_b64_e32 v[158:159], 0x200
	v_mov_b64_e32 v[160:161], 0x1ff
	v_add_u32_e32 v177, s85, v175
	v_add_u32_e32 v178, s86, v175
	v_add_u32_e32 v179, 0, v13
	s_mov_b32 s87, 0xff61b1e6
	s_mov_b32 s34, 0x3fb8aa3b
	v_lshlrev_b32_e32 v156, 1, v0
	s_mov_b32 s88, 0
	s_barrier
	s_waitcnt vmcnt(0)
	s_branch .LBB0_875

; #define PG8_STAGE(bufoff, gbase, voff) do { _Pragma("unroll") for (int _i = 0; _i < 2; ++_i) \
;         __builtin_amdgcn_global_load_lds((const unsigned*)((const char*)(gbase) + (voff)[_i]), (LAS unsigned*)(lds + (bufoff) + ldsw + _i * 8192), 16, 0, 0); } while (0)
; #define PG8_WAIT_V(n) asm volatile("s_waitcnt vmcnt(" #n ")" ::: "memory")
; #define PG8_BAR __builtin_amdgcn_s_barrier()
; template <class GEO, class Epi>
; __device__ __forceinline__ void gemm_phase(LAS unsigned char* lds, const Gemm g, const StaticOrder& S, const Epi& E) {
;     ...
;     for (int i = 0; i < 2; ++i) { int R, C; stage_rc(tid * 16 + i * 8192, R, C); const int Rb = Epi::PERM ? ((R & ~31) + perm32(R & 31)) : R;
;         voffA[i] = (unsigned)(R * GEO::LDA + C) * 2u; voffB[i] = (unsigned)(Rb * GEO::LDB + C) * 2u; }
;     const size_t kstep = (size_t)(BK * 2);
;     constexpr size_t hstepA = (size_t)HALF * GEO::LDA * 2, hstepB = (size_t)HALF * GEO::LDB * 2;
;     const unsigned ldsw = (unsigned)wid * 1024u;
;     const int aoff = lds_byte(wr * 64 + fr, fq * 8), boff = lds_byte(wc * 32 + fr, fq * 8);
;     ...
;     PG8_STAGE(PG8_SB(0, 0), cB, voffB); PG8_STAGE(PG8_SB(0, 1), cB + hstepB, voffB); PG8_STAGE(PG8_SA(0, 0), cA, voffA); PG8_STAGE(PG8_SA(0, 1), cA + hstepA, voffA);
;     if (wr == 1) PG8_BAR;
;     PG8_WAIT_V(2); PG8_BAR;
;     PG8_STAGE(PG8_SB(1, 0), cB + kstep, voffB); PG8_STAGE(PG8_SA(1, 0), cA + kstep, voffA); PG8_STAGE(PG8_SB(1, 1), cB + hstepB + kstep, voffB);
;     PG8_WAIT_V(6); PG8_BAR;
.LBB0_979:
	v_bfe_u32 v17, v11, 4, 2
	v_lshrrev_b32_e32 v15, 4, v11
	v_and_b32_e32 v16, 15, v11
	v_lshlrev_b32_e32 v19, 4, v17
	v_lshlrev_b32_e32 v11, 2, v11
	s_and_b32 s19, s15, 3
	v_lshl_or_b32 v19, v16, 6, v19
	s_lshl_b32 s7, s18, 13
	v_and_b32_e32 v11, 32, v11
	s_mov_b64 s[34:35], 0x80
	v_bitop3_b32 v20, v19, s7, v11 bitop3:0xde
	s_lshl_b32 s7, s19, 12
	s_add_i32 m0, s1, 0x18000
	v_lshl_add_u64 v[6:7], v[6:7], 0, s[34:35]
	v_bitop3_b32 v149, v19, s7, v11 bitop3:0xde
	global_load_lds_dwordx4 v[6:7], off
	v_lshl_add_u64 v[4:5], v[4:5], 0, s[34:35]
	s_add_i32 m0, s1, 0x1a000
	s_add_i32 s7, s1, 0x8000
	s_add_i32 s12, s1, 0xa000
	global_load_lds_dwordx4 v[4:5], off
	v_lshl_add_u64 v[0:1], v[0:1], 0, s[34:35]
	s_mov_b32 m0, s7
	s_add_u32 s20, s54, 0x100080
	global_load_lds_dwordx4 v[0:1], off
	v_lshl_add_u64 v[0:1], v[2:3], 0, s[34:35]
	s_mov_b32 m0, s12
	s_addc_u32 s21, s55, 0
	global_load_lds_dwordx4 v[0:1], off
	s_add_i32 m0, s1, 0x1c000
	v_lshl_add_u64 v[0:1], s[20:21], 0, v[130:131]
	global_load_lds_dwordx4 v[0:1], off
	v_lshl_add_u64 v[0:1], s[20:21], 0, v[134:135]
	s_add_i32 m0, s1, 0x1e000
	s_cmpk_lt_u32 s13, 0x100
	global_load_lds_dwordx4 v[0:1], off
	s_waitcnt vmcnt(8)
	s_barrier
	v_bitop3_b32 v0, s15, v15, 3 bitop3:0xa8
	v_cmp_eq_u32_e64 s[42:43], 0, v0
	v_lshlrev_b32_e32 v0, 14, v8
	v_and_b32_e32 v0, 0xffff8000, v0
	v_lshl_add_u32 v0, v9, 11, v0
	v_and_b32_e32 v1, 1, v8
	v_lshl_or_b32 v0, v1, 6, v0
	v_lshl_add_u32 v136, v10, 1, v0
	v_lshlrev_b32_e32 v0, 14, v12
	s_cselect_b64 s[20:21], -1, 0
	s_lshl_b32 s13, s18, 10
	v_and_b32_e32 v0, 0xffff8000, v0
	v_lshlrev_b32_e32 v18, 3, v17
	s_waitcnt vmcnt(6)
	s_add_i32 s60, s13, 0
	v_lshl_add_u32 v0, v13, 11, v0
	v_and_b32_e32 v1, 1, v12
	v_lshl_or_b32 v150, s19, 5, v18
	s_lshl_b32 s19, s19, 2
	s_add_i32 s13, s60, 0x20000
	v_lshl_or_b32 v0, v1, 6, v0
	s_add_i32 s61, 0, 0x10000
	s_add_i32 s62, 0, 0x14000
	v_lshl_or_b32 v148, s18, 6, v16
	v_cmp_eq_u32_e64 s[40:41], 0, v17
	s_add_i32 s18, s13, s19
	v_lshlrev_b32_e32 v151, 4, v16
	s_add_i32 s19, s60, 0x20b00
	s_add_i32 s33, s60, 0x20a00
	s_add_i32 s36, s60, 0x20900
	s_add_i32 s37, s60, 0x20800
	s_add_i32 s58, s60, 0x20300
	s_add_i32 s59, s60, 0x20200
	s_add_i32 s60, s60, 0x20100
	v_mov_b32_e32 v137, v131
	v_lshl_add_u32 v138, v14, 1, v0
	v_mov_b32_e32 v139, v131
	v_mov_b64_e32 v[140:141], 0x200
	v_mov_b64_e32 v[142:143], 0x1ff
	v_add_u32_e32 v152, s61, v149
	v_add_u32_e32 v153, s62, v149
	v_add_u32_e32 v154, 0, v20
	s_mov_b32 s63, 0
	s_barrier
	s_branch .LBB0_982

; #define PG8_STAGE(bufoff, gbase, voff) do { _Pragma("unroll") for (int _i = 0; _i < 2; ++_i) \
;         __builtin_amdgcn_global_load_lds((const unsigned*)((const char*)(gbase) + (voff)[_i]), (LAS unsigned*)(lds + (bufoff) + ldsw + _i * 8192), 16, 0, 0); } while (0)
; #define PG8_WAIT_V(n) asm volatile("s_waitcnt vmcnt(" #n ")" ::: "memory")
; #define PG8_BAR __builtin_amdgcn_s_barrier()
; template <class GEO, class Epi>
; __device__ __forceinline__ void gemm_phase(LAS unsigned char* lds, const Gemm g, const StaticOrder& S, const Epi& E) {
;     ...
;     for (int i = 0; i < 2; ++i) { int R, C; stage_rc(tid * 16 + i * 8192, R, C); const int Rb = Epi::PERM ? ((R & ~31) + perm32(R & 31)) : R;
;         voffA[i] = (unsigned)(R * GEO::LDA + C) * 2u; voffB[i] = (unsigned)(Rb * GEO::LDB + C) * 2u; }
;     const size_t kstep = (size_t)(BK * 2);
;     constexpr size_t hstepA = (size_t)HALF * GEO::LDA * 2, hstepB = (size_t)HALF * GEO::LDB * 2;
;     const unsigned ldsw = (unsigned)wid * 1024u;
;     const int aoff = lds_byte(wr * 64 + fr, fq * 8), boff = lds_byte(wc * 32 + fr, fq * 8);
;     ...
;     PG8_STAGE(PG8_SB(0, 0), cB, voffB); PG8_STAGE(PG8_SB(0, 1), cB + hstepB, voffB); PG8_STAGE(PG8_SA(0, 0), cA, voffA); PG8_STAGE(PG8_SA(0, 1), cA + hstepA, voffA);
;     if (wr == 1) PG8_BAR;
;     PG8_WAIT_V(2); PG8_BAR;
;     PG8_STAGE(PG8_SB(1, 0), cB + kstep, voffB); PG8_STAGE(PG8_SA(1, 0), cA + kstep, voffA); PG8_STAGE(PG8_SB(1, 1), cB + hstepB + kstep, voffB);
;     PG8_WAIT_V(6); PG8_BAR;
.LBB0_1065:
	v_lshrrev_b32_e32 v16, 1, v14
	v_and_b32_e32 v16, 24, v16
	s_lshl_b32 s7, s7, 5
	v_and_b32_e32 v15, 15, v14
	v_lshlrev_b32_e32 v17, 1, v16
	v_lshlrev_b32_e32 v14, 2, v14
	s_and_b32 s14, s7, 0x60
	s_mov_b64 s[24:25], 0x80
	v_lshl_or_b32 v148, s12, 6, v15
	v_lshl_or_b32 v15, v15, 6, v17
	s_lshl_b32 s12, s12, 13
	v_and_b32_e32 v14, 32, v14
	s_lshl_b32 s7, s14, 7
	s_add_i32 m0, s1, 0x18000
	v_lshl_add_u64 v[6:7], v[6:7], 0, s[24:25]
	v_bitop3_b32 v17, v15, s12, v14 bitop3:0xde
	v_bitop3_b32 v149, v15, s7, v14 bitop3:0xde
	global_load_lds_dwordx4 v[6:7], off
	v_lshl_add_u64 v[4:5], v[4:5], 0, s[24:25]
	s_add_i32 m0, s1, 0x1a000
	s_add_i32 s7, s1, 0x8000
	s_add_i32 s12, s1, 0xa000
	global_load_lds_dwordx4 v[4:5], off
	v_lshl_add_u64 v[0:1], v[0:1], 0, s[24:25]
	s_mov_b32 m0, s7
	s_add_u32 s18, s44, 0x40080
	global_load_lds_dwordx4 v[0:1], off
	v_lshl_add_u64 v[0:1], v[2:3], 0, s[24:25]
	s_mov_b32 m0, s12
	s_addc_u32 s19, s45, 0
	global_load_lds_dwordx4 v[0:1], off
	s_add_i32 m0, s1, 0x1c000
	v_lshl_add_u64 v[0:1], s[18:19], 0, v[132:133]
	global_load_lds_dwordx4 v[0:1], off
	v_lshl_add_u64 v[0:1], s[18:19], 0, v[128:129]
	s_add_i32 m0, s1, 0x1e000
	s_cmpk_lt_u32 s13, 0x100
	global_load_lds_dwordx4 v[0:1], off
	s_waitcnt vmcnt(8)
	s_barrier
	v_lshlrev_b32_e32 v0, 14, v12
	v_and_b32_e32 v0, 0xffff8000, v0
	v_lshl_add_u32 v0, v11, 11, v0
	v_and_b32_e32 v1, 1, v12
	v_lshl_or_b32 v0, v1, 6, v0
	v_lshl_add_u32 v136, v13, 1, v0
	v_lshlrev_b32_e32 v0, 14, v8
	v_and_b32_e32 v0, 0xffff8000, v0
	s_waitcnt vmcnt(6)
	v_lshl_add_u32 v0, v9, 11, v0
	v_and_b32_e32 v1, 1, v8
	s_cselect_b64 s[28:29], -1, 0
	v_lshl_or_b32 v0, v1, 6, v0
	s_add_i32 s13, 0, 0x10000
	s_add_i32 s18, 0, 0x14000
	v_or_b32_e32 v150, s14, v16
	v_mov_b32_e32 v137, v133
	v_lshl_add_u32 v138, v10, 1, v0
	v_mov_b32_e32 v139, v133
	v_mov_b64_e32 v[140:141], 0x800
	v_mov_b64_e32 v[142:143], 0x7ff
	v_add_u32_e32 v151, s13, v149
	v_add_u32_e32 v152, s18, v149
	v_add_u32_e32 v153, 0, v17
	v_mov_b32_e32 v154, 0x358637bd
	s_mov_b32 s19, 0x800000
	s_mov_b32 s33, 0
	s_barrier
	s_branch .LBB0_1068

; #define PG8_STAGE(bufoff, gbase, voff) do { _Pragma("unroll") for (int _i = 0; _i < 2; ++_i) \
;         __builtin_amdgcn_global_load_lds((const unsigned*)((const char*)(gbase) + (voff)[_i]), (LAS unsigned*)(lds + (bufoff) + ldsw + _i * 8192), 16, 0, 0); } while (0)
; #define PG8_WAIT_V(n) asm volatile("s_waitcnt vmcnt(" #n ")" ::: "memory")
; #define PG8_BAR __builtin_amdgcn_s_barrier()
; template <class GEO, class Epi>
; __device__ __forceinline__ void gemm_phase(LAS unsigned char* lds, const Gemm g, const StaticOrder& S, const Epi& E) {
;     ...
;     for (int i = 0; i < 2; ++i) { int R, C; stage_rc(tid * 16 + i * 8192, R, C); const int Rb = Epi::PERM ? ((R & ~31) + perm32(R & 31)) : R;
;         voffA[i] = (unsigned)(R * GEO::LDA + C) * 2u; voffB[i] = (unsigned)(Rb * GEO::LDB + C) * 2u; }
;     const size_t kstep = (size_t)(BK * 2);
;     constexpr size_t hstepA = (size_t)HALF * GEO::LDA * 2, hstepB = (size_t)HALF * GEO::LDB * 2;
;     const unsigned ldsw = (unsigned)wid * 1024u;
;     const int aoff = lds_byte(wr * 64 + fr, fq * 8), boff = lds_byte(wc * 32 + fr, fq * 8);
;     ...
;     PG8_STAGE(PG8_SB(0, 0), cB, voffB); PG8_STAGE(PG8_SB(0, 1), cB + hstepB, voffB); PG8_STAGE(PG8_SA(0, 0), cA, voffA); PG8_STAGE(PG8_SA(0, 1), cA + hstepA, voffA);
;     if (wr == 1) PG8_BAR;
;     PG8_WAIT_V(2); PG8_BAR;
;     PG8_STAGE(PG8_SB(1, 0), cB + kstep, voffB); PG8_STAGE(PG8_SA(1, 0), cA + kstep, voffA); PG8_STAGE(PG8_SB(1, 1), cB + hstepB + kstep, voffB);
;     PG8_WAIT_V(6); PG8_BAR;
.LBB0_1138:
	s_lshl_b32 s1, s1, 5
	s_mov_b64 s[8:9], 0x80
	s_and_b32 s1, s1, 0x60
	s_add_i32 m0, s21, 0x18000
	v_lshl_add_u64 v[6:7], v[6:7], 0, s[8:9]
	s_lshl_b32 s4, s0, 13
	s_lshl_b32 s13, s1, 7
	global_load_lds_dwordx4 v[6:7], off
	v_lshl_add_u64 v[4:5], v[4:5], 0, s[8:9]
	s_add_i32 m0, s21, 0x1a000
	s_add_i32 s35, s21, 0x8000
	s_add_i32 s36, s21, 0xa000
	global_load_lds_dwordx4 v[4:5], off
	v_lshl_add_u64 v[0:1], v[0:1], 0, s[8:9]
	s_mov_b32 m0, s35
	s_add_u32 s14, s24, 0x100080
	global_load_lds_dwordx4 v[0:1], off
	v_lshl_add_u64 v[0:1], v[2:3], 0, s[8:9]
	s_mov_b32 m0, s36
	s_addc_u32 s15, s25, 0
	global_load_lds_dwordx4 v[0:1], off
	s_add_i32 m0, s21, 0x1c000
	v_lshl_add_u64 v[0:1], s[14:15], 0, v[130:131]
	global_load_lds_dwordx4 v[0:1], off
	v_lshl_add_u64 v[0:1], s[14:15], 0, v[134:135]
	s_add_i32 m0, s21, 0x1e000
	s_cmpk_lt_u32 s12, 0x100
	global_load_lds_dwordx4 v[0:1], off
	s_waitcnt vmcnt(8)
	s_barrier
	v_lshrrev_b32_e32 v1, 1, v208
	v_and_b32_e32 v1, 24, v1
	v_and_b32_e32 v0, 15, v208
	v_lshlrev_b32_e32 v2, 1, v1
	v_lshl_or_b32 v148, s0, 6, v0
	v_lshl_or_b32 v0, v0, 6, v2
	v_lshlrev_b32_e32 v2, 2, v208
	v_and_b32_e32 v2, 32, v2
	v_bitop3_b32 v3, v0, s4, v2 bitop3:0xde
	v_bitop3_b32 v149, v0, s13, v2 bitop3:0xde
	v_lshlrev_b32_e32 v0, 16, v8
	v_and_b32_e32 v0, 0xfffe0000, v0
	v_or_b32_e32 v150, s1, v1
	v_lshl_add_u32 v0, v9, 13, v0
	v_and_b32_e32 v1, 1, v8
	v_lshl_or_b32 v0, v1, 6, v0
	v_lshl_add_u32 v136, v10, 1, v0
	v_lshlrev_b32_e32 v0, 16, v11
	v_and_b32_e32 v0, 0xfffe0000, v0
	s_waitcnt vmcnt(6)
	v_lshl_add_u32 v0, v12, 13, v0
	v_and_b32_e32 v1, 1, v11
	s_cselect_b64 s[12:13], -1, 0
	v_lshl_or_b32 v0, v1, 6, v0
	s_add_i32 s37, 0, 0x10000
	s_add_i32 s38, 0, 0x14000
	v_mov_b32_e32 v137, v131
	v_lshl_add_u32 v138, v13, 1, v0
	v_mov_b32_e32 v139, v131
	v_mov_b64_e32 v[140:141], 0x200
	v_mov_b64_e32 v[142:143], 0x1ff
	v_add_u32_e32 v151, s37, v149
	v_add_u32_e32 v152, s38, v149
	v_add_u32_e32 v153, 0, v3
	s_mov_b32 s39, 0
	s_barrier
	s_branch .LBB0_1141
